# k-blocked weight layout for ALL seven regular GEMM loops (adds OUTPROJ WNO/WDO and FFN2 WFO K=2752): every LDS-DMA weight piece is one contiguous KiB
# speedup vs baseline: 1.0576x; 1.0250x over previous
.LBB0_118:
	s_or_b64 exec, exec, s[0:1]
	s_waitcnt vmcnt(1)
	v_mov_b32_e32 v14, v224
	s_lshl_b32 s0, s87, 8
	v_readfirstlane_b32 s42, v14
	v_bfe_u32 v15, v14, 4, 2
	v_sub_u32_e32 v16, 0, v15
	s_and_b32 s13, s42, 0xffffffc0
	v_bfe_u32 v10, v14, 2, 4
	v_xor_b32_e32 v0, v14, v16
	s_add_i32 s13, s13, s0
	v_or_b32_e32 v11, s13, v10
	v_lshlrev_b32_e32 v0, 4, v0
	s_lshl_b32 s12, s88, 7
	s_ashr_i32 s43, s42, 6
	v_and_b32_e32 v0, 48, v0
	v_min_i32_e32 v4, 0x3ff, v11
	v_or_b32_e32 v6, 16, v11
	v_or_b32_e32 v8, 32, v11
	v_or_b32_e32 v11, 48, v11
	v_lshl_add_u64 v[2:3], s[46:47], 0, v[0:1]
	v_min_i32_e32 v6, 0x3ff, v6
	v_min_i32_e32 v8, 0x3ff, v8
	v_min_i32_e32 v11, 0x3ff, v11
	s_lshl_b32 s13, s43, 1
	v_or_b32_e32 v17, s12, v10
	v_mad_i64_i32 v[4:5], s[14:15], v4, 64, v[2:3]
	v_mad_i64_i32 v[6:7], s[14:15], v6, 64, v[2:3]
	v_mad_i64_i32 v[8:9], s[14:15], v8, 64, v[2:3]
	v_mad_i64_i32 v[2:3], s[14:15], v11, 64, v[2:3]
	v_lshl_add_u64 v[10:11], s[4:5], 0, v[0:1]
	v_lshl_add_u32 v0, s43, 5, v17
	s_movk_i32 s69, 0xac0
	s_lshl_b32 s68, s13, 10
	s_or_b32 s13, s13, 1
	v_mad_i64_i32 v[130:131], s[14:15], v0, s69, 0
	v_lshl_add_u32 v0, s13, 4, v17
	s_waitcnt vmcnt(0)
	s_barrier
	v_lshl_add_u64 v[12:13], v[130:131], 1, v[10:11]
	s_mov_b32 s14, m0
	s_mov_b32 m0, s68
	s_nop 0
	global_load_lds_dwordx4 v[12:13], off
	s_mov_b32 m0, s14
	s_lshl_b32 s13, s13, 10
	v_mad_i64_i32 v[132:133], s[14:15], v0, s69, 0
	v_lshl_add_u64 v[10:11], v[132:133], 1, v[10:11]
	s_mov_b32 s14, m0
	s_mov_b32 m0, s13
	s_nop 0
	global_load_lds_dwordx4 v[10:11], off
	s_mov_b32 m0, s14
	s_lshl_b32 s15, s43, 12
	s_add_i32 s14, s15, 0x2000
	s_mov_b32 s69, m0
	s_mov_b32 m0, s14
	s_nop 0
	global_load_lds_dwordx4 v[4:5], off
	s_mov_b32 m0, s69
	s_add_i32 s69, s15, 0x2400
	s_mov_b32 s70, m0
	s_mov_b32 m0, s69
	s_nop 0
	global_load_lds_dwordx4 v[6:7], off
	s_mov_b32 m0, s70
	s_add_i32 s69, s15, 0x2800
	s_mov_b32 s70, m0
	s_mov_b32 m0, s69
	s_nop 0
	global_load_lds_dwordx4 v[8:9], off
	s_mov_b32 m0, s70
	s_add_i32 s69, s15, 0x2c00
	s_mov_b32 s70, m0
	s_mov_b32 m0, s69
	s_nop 0
	global_load_lds_dwordx4 v[2:3], off
	s_mov_b32 m0, s70
	v_lshl_add_u64 v[12:13], v[12:13], 0, 64
	s_addk_i32 s68, 0x6000
	s_mov_b32 s69, m0
	s_mov_b32 m0, s68
	s_nop 0
	global_load_lds_dwordx4 v[12:13], off
	s_mov_b32 m0, s69
	v_lshl_add_u64 v[10:11], v[10:11], 0, 64
	s_add_i32 s68, s13, 0x6000
	s_mov_b32 s69, m0
	s_mov_b32 m0, s68
	s_nop 0
	global_load_lds_dwordx4 v[10:11], off
	s_mov_b32 m0, s69
	s_mov_b32 s100, 0x10000
	s_mov_b32 s101, 0
	v_lshl_add_u64 v[10:11], v[4:5], 0, s[100:101]
	s_add_i32 s68, s15, 0x8000
	s_mov_b32 s69, m0
	s_mov_b32 m0, s68
	s_nop 0
	global_load_lds_dwordx4 v[10:11], off
	s_mov_b32 m0, s69
	v_lshrrev_b32_e32 v0, 2, v14
	v_lshl_add_u64 v[10:11], v[6:7], 0, s[100:101]
	s_add_i32 s68, s15, 0x8400
	s_mov_b32 s69, m0
	s_mov_b32 m0, s68
	s_nop 0
	global_load_lds_dwordx4 v[10:11], off
	s_mov_b32 m0, s69
	v_sub_u32_e32 v0, 0, v0
	v_lshl_add_u64 v[10:11], v[8:9], 0, s[100:101]
	s_add_i32 s68, s15, 0x8800
	s_mov_b32 s69, m0
	s_mov_b32 m0, s68
	s_nop 0
	global_load_lds_dwordx4 v[10:11], off
	s_mov_b32 m0, s69
	s_add_i32 s15, s15, 0x8c00
	v_bitop3_b32 v0, v15, v0, 3 bitop3:0x78
	v_lshl_add_u64 v[10:11], v[2:3], 0, s[100:101]
	s_mov_b32 s68, m0
	s_mov_b32 m0, s15
	s_nop 0
	global_load_lds_dwordx4 v[10:11], off
	s_mov_b32 m0, s68
	v_lshlrev_b32_e32 v144, 4, v0
	v_and_b32_e32 v0, 15, v14
	s_and_b32 s15, s42, 0x3ffff80
	v_and_or_b32 v10, s42, 64, v0
	v_or_b32_e32 v0, s15, v0
	v_lshlrev_b32_e32 v145, 6, v0
	v_bitop3_b32 v0, v14, 3, v16 bitop3:0x48
	s_mov_b32 s100, 0x20000
	v_lshl_add_u64 v[134:135], v[2:3], 0, s[100:101]
	v_lshlrev_b32_e32 v0, 4, v0
	v_mov_b32_e32 v2, 0
	s_mov_b32 s1, 0
	v_lshlrev_b32_e32 v146, 6, v10
	s_lshl_b32 s15, s43, 11
	v_lshl_add_u64 v[136:137], v[8:9], 0, s[100:101]
	v_lshl_add_u64 v[138:139], v[6:7], 0, s[100:101]
	v_lshl_add_u64 v[140:141], v[4:5], 0, s[100:101]
	v_lshl_add_u64 v[142:143], s[56:57], 0, v[0:1]
	s_mov_b64 s[42:43], 0
	v_mov_b32_e32 v3, v2
	v_mov_b32_e32 v4, v2
	v_mov_b32_e32 v5, v2
	v_mov_b32_e32 v6, v2
	v_mov_b32_e32 v7, v2
	v_mov_b32_e32 v8, v2
	v_mov_b32_e32 v9, v2
	v_mov_b32_e32 v10, v2
	v_mov_b32_e32 v11, v2
	v_mov_b32_e32 v12, v2
	v_mov_b32_e32 v13, v2
	v_mov_b32_e32 v14, v2
	v_mov_b32_e32 v15, v2
	v_mov_b32_e32 v16, v2
	v_mov_b32_e32 v17, v2
	s_waitcnt vmcnt(21)
	v_mov_b32_e32 v18, v2
	v_mov_b32_e32 v19, v2
	v_mov_b32_e32 v20, v2
	v_mov_b32_e32 v21, v2
	s_waitcnt vmcnt(20)
	v_mov_b32_e32 v22, v2
	v_mov_b32_e32 v23, v2
	v_mov_b32_e32 v24, v2
	v_mov_b32_e32 v25, v2
	v_mov_b32_e32 v26, v2
	v_mov_b32_e32 v27, v2
	v_mov_b32_e32 v28, v2
	v_mov_b32_e32 v29, v2
	s_waitcnt vmcnt(19)
	v_mov_b32_e32 v30, v2
	v_mov_b32_e32 v31, v2
	v_mov_b32_e32 v32, v2
	v_mov_b32_e32 v33, v2
	v_mov_b32_e32 v34, v2
	v_mov_b32_e32 v35, v2
	v_mov_b32_e32 v36, v2
	v_mov_b32_e32 v37, v2
	v_mov_b32_e32 v38, v2
	v_mov_b32_e32 v39, v2
	v_mov_b32_e32 v40, v2
	v_mov_b32_e32 v41, v2
	s_waitcnt vmcnt(18)
	v_mov_b32_e32 v42, v2
	v_mov_b32_e32 v43, v2
	v_mov_b32_e32 v44, v2
	v_mov_b32_e32 v45, v2
	s_waitcnt vmcnt(0)
	v_mov_b32_e32 v46, v2
	v_mov_b32_e32 v47, v2
	v_mov_b32_e32 v48, v2
	v_mov_b32_e32 v49, v2
	s_waitcnt vmcnt(17)
	v_mov_b32_e32 v50, v2
	v_mov_b32_e32 v51, v2
	v_mov_b32_e32 v52, v2
	v_mov_b32_e32 v53, v2
	v_mov_b32_e32 v54, v2
	v_mov_b32_e32 v55, v2
	v_mov_b32_e32 v56, v2
	v_mov_b32_e32 v57, v2
	v_mov_b32_e32 v58, v2
	v_mov_b32_e32 v59, v2
	v_mov_b32_e32 v60, v2
	v_mov_b32_e32 v61, v2
	s_waitcnt vmcnt(16)
	v_mov_b32_e32 v62, v2
	v_mov_b32_e32 v63, v2
	v_mov_b32_e32 v64, v2
	v_mov_b32_e32 v65, v2
	v_mov_b32_e32 v66, v2
	v_mov_b32_e32 v67, v2
	v_mov_b32_e32 v68, v2
	v_mov_b32_e32 v69, v2
	v_mov_b32_e32 v70, v2
	v_mov_b32_e32 v71, v2
	v_mov_b32_e32 v72, v2
	v_mov_b32_e32 v73, v2
	v_mov_b32_e32 v74, v2
	v_mov_b32_e32 v75, v2
	v_mov_b32_e32 v76, v2
	v_mov_b32_e32 v77, v2
	v_mov_b32_e32 v78, v2
	v_mov_b32_e32 v79, v2
	v_mov_b32_e32 v80, v2
	v_mov_b32_e32 v81, v2
	v_mov_b32_e32 v82, v2
	v_mov_b32_e32 v83, v2
	v_mov_b32_e32 v84, v2
	v_mov_b32_e32 v85, v2
	v_mov_b32_e32 v86, v2
	v_mov_b32_e32 v87, v2
	v_mov_b32_e32 v88, v2
	v_mov_b32_e32 v89, v2
	v_mov_b32_e32 v90, v2
	v_mov_b32_e32 v91, v2
	v_mov_b32_e32 v92, v2
	v_mov_b32_e32 v93, v2
	v_mov_b32_e32 v94, v2
	v_mov_b32_e32 v95, v2
	v_mov_b32_e32 v96, v2
	v_mov_b32_e32 v97, v2
	v_mov_b32_e32 v98, v2
	v_mov_b32_e32 v99, v2
	v_mov_b32_e32 v100, v2
	v_mov_b32_e32 v101, v2
	v_mov_b32_e32 v102, v2
	v_mov_b32_e32 v103, v2
	v_mov_b32_e32 v104, v2
	v_mov_b32_e32 v105, v2
	v_mov_b32_e32 v106, v2
	v_mov_b32_e32 v107, v2
	v_mov_b32_e32 v108, v2
	v_mov_b32_e32 v109, v2
	v_mov_b32_e32 v110, v2
	v_mov_b32_e32 v111, v2
	v_mov_b32_e32 v112, v2
	v_mov_b32_e32 v113, v2
	v_mov_b32_e32 v114, v2
	v_mov_b32_e32 v115, v2
	v_mov_b32_e32 v116, v2
	v_mov_b32_e32 v117, v2
	v_mov_b32_e32 v118, v2
	v_mov_b32_e32 v119, v2
	v_mov_b32_e32 v120, v2
	v_mov_b32_e32 v121, v2
	v_mov_b32_e32 v122, v2
	v_mov_b32_e32 v123, v2
	v_mov_b32_e32 v124, v2
	v_mov_b32_e32 v125, v2
	v_mov_b32_e32 v126, v2
	v_mov_b32_e32 v127, v2
	v_mov_b32_e32 v128, v2
	v_mov_b32_e32 v129, v2
.LBB0_119:
	s_mul_i32 s100, s42, 0x400
	s_mul_i32 s68, s1, 0x6000
	s_add_i32 s69, s68, 0xffffa000
	s_cmp_gt_i32 s1, 0
	s_waitcnt vmcnt(6)
	s_cselect_b32 s69, s69, 0xc000
	s_waitcnt lgkmcnt(0)
	s_barrier
	s_setprio 2
	v_or_b32_e32 v0, s68, v146
	v_add_u32_e32 v0, v0, v144
	v_add3_u32 v212, s68, v145, v144
	ds_read_b128 v[164:167], v212 offset:8192
	ds_read_b128 v[148:151], v0
	ds_read_b128 v[152:155], v0 offset:1024
	ds_read_b128 v[156:159], v0 offset:2048
	ds_read_b128 v[160:163], v0 offset:3072
	ds_read_b128 v[168:171], v212 offset:9216
	ds_read_b128 v[172:175], v212 offset:10240
	ds_read_b128 v[176:179], v212 offset:11264
	ds_read_b128 v[180:183], v212 offset:12288
	ds_read_b128 v[184:187], v212 offset:13312
	ds_read_b128 v[188:191], v212 offset:14336
	ds_read_b128 v[192:195], v212 offset:15360
	v_lshl_add_u64 v[212:213], v[142:143], 0, s[42:43]
	v_lshl_add_u64 v[212:213], v[130:131], 1, v[212:213]
	s_add_i32 s70, s69, s15
	s_mov_b32 m0, s70
	s_nop 0
	global_load_lds_dwordx4 v[212:213], off
	v_lshl_add_u64 v[212:213], v[142:143], 0, s[42:43]
	v_lshl_add_u64 v[212:213], v[132:133], 1, v[212:213]
	s_add_i32 s70, s69, s13
	s_mov_b32 m0, s70
	s_nop 0
	global_load_lds_dwordx4 v[212:213], off
	s_add_i32 s69, s14, s69
	v_lshl_add_u64 v[212:213], v[140:141], 0, s[100:101]
	s_mov_b32 m0, s69
	s_nop 0
	global_load_lds_dwordx4 v[212:213], off
	v_lshl_add_u64 v[212:213], v[138:139], 0, s[100:101]
	s_add_i32 s70, s69, 0x400
	s_mov_b32 m0, s70
	s_nop 0
	global_load_lds_dwordx4 v[212:213], off
	v_lshl_add_u64 v[212:213], v[136:137], 0, s[100:101]
	s_add_i32 s70, s69, 0x800
	s_mov_b32 m0, s70
	s_nop 0
	global_load_lds_dwordx4 v[212:213], off
	v_lshl_add_u64 v[212:213], v[134:135], 0, s[100:101]
	s_addk_i32 s69, 0xc00
	s_mov_b32 m0, s69
	s_nop 0
	global_load_lds_dwordx4 v[212:213], off
	s_setprio 0
	s_waitcnt lgkmcnt(10)
	v_mfma_f32_16x16x32_bf16 v[126:129], v[164:167], v[148:151], v[126:129]
	s_waitcnt lgkmcnt(9)
	v_mfma_f32_16x16x32_bf16 v[122:125], v[164:167], v[152:155], v[122:125]
	s_waitcnt lgkmcnt(8)
	v_mfma_f32_16x16x32_bf16 v[118:121], v[164:167], v[156:159], v[118:121]
	s_waitcnt lgkmcnt(7)
	v_mfma_f32_16x16x32_bf16 v[114:117], v[164:167], v[160:163], v[114:117]
	s_waitcnt lgkmcnt(6)
	v_mfma_f32_16x16x32_bf16 v[110:113], v[168:171], v[148:151], v[110:113]
	v_mfma_f32_16x16x32_bf16 v[106:109], v[168:171], v[152:155], v[106:109]
	v_mfma_f32_16x16x32_bf16 v[102:105], v[168:171], v[156:159], v[102:105]
	v_mfma_f32_16x16x32_bf16 v[98:101], v[168:171], v[160:163], v[98:101]
	s_waitcnt lgkmcnt(5)
	v_mfma_f32_16x16x32_bf16 v[94:97], v[172:175], v[148:151], v[94:97]
	v_mfma_f32_16x16x32_bf16 v[90:93], v[172:175], v[152:155], v[90:93]
	v_mfma_f32_16x16x32_bf16 v[86:89], v[172:175], v[156:159], v[86:89]
	v_mfma_f32_16x16x32_bf16 v[82:85], v[172:175], v[160:163], v[82:85]
	s_waitcnt lgkmcnt(4)
	v_mfma_f32_16x16x32_bf16 v[78:81], v[176:179], v[148:151], v[78:81]
	v_mfma_f32_16x16x32_bf16 v[74:77], v[176:179], v[152:155], v[74:77]
	v_mfma_f32_16x16x32_bf16 v[70:73], v[176:179], v[156:159], v[70:73]
	v_mfma_f32_16x16x32_bf16 v[66:69], v[176:179], v[160:163], v[66:69]
	s_waitcnt lgkmcnt(3)
	v_mfma_f32_16x16x32_bf16 v[62:65], v[180:183], v[148:151], v[62:65]
	v_mfma_f32_16x16x32_bf16 v[58:61], v[180:183], v[152:155], v[58:61]
	v_mfma_f32_16x16x32_bf16 v[54:57], v[180:183], v[156:159], v[54:57]
	v_mfma_f32_16x16x32_bf16 v[50:53], v[180:183], v[160:163], v[50:53]
	s_waitcnt lgkmcnt(2)
	v_mfma_f32_16x16x32_bf16 v[46:49], v[184:187], v[148:151], v[46:49]
	v_mfma_f32_16x16x32_bf16 v[42:45], v[184:187], v[152:155], v[42:45]
	v_mfma_f32_16x16x32_bf16 v[38:41], v[184:187], v[156:159], v[38:41]
	v_mfma_f32_16x16x32_bf16 v[34:37], v[184:187], v[160:163], v[34:37]
	s_waitcnt lgkmcnt(1)
	v_mfma_f32_16x16x32_bf16 v[30:33], v[188:191], v[148:151], v[30:33]
	v_mfma_f32_16x16x32_bf16 v[26:29], v[188:191], v[152:155], v[26:29]
	v_mfma_f32_16x16x32_bf16 v[22:25], v[188:191], v[156:159], v[22:25]
	v_mfma_f32_16x16x32_bf16 v[18:21], v[188:191], v[160:163], v[18:21]
	s_waitcnt lgkmcnt(0)
	v_mfma_f32_16x16x32_bf16 v[14:17], v[192:195], v[148:151], v[14:17]
	v_mfma_f32_16x16x32_bf16 v[10:13], v[192:195], v[152:155], v[10:13]
	v_mfma_f32_16x16x32_bf16 v[6:9], v[192:195], v[156:159], v[6:9]
	v_mfma_f32_16x16x32_bf16 v[2:5], v[192:195], v[160:163], v[2:5]
	s_add_i32 s68, s1, 1
	s_cmp_lg_u32 s1, 2
	s_cselect_b32 s1, s68, 0
	s_add_u32 s42, s42, 64
	s_addc_u32 s43, s43, 0
	s_cmpk_eq_i32 s42, 0x1500
	s_cbranch_scc0 .LBB0_119
	s_waitcnt vmcnt(6)
	v_add_u32_e32 v0, v146, v144
	v_add_u32_e32 v221, v145, v144
	s_waitcnt lgkmcnt(0)
	s_barrier
	ds_read_b128 v[130:133], v0
	ds_read_b128 v[134:137], v0 offset:1024
	ds_read_b128 v[138:141], v0 offset:2048
	ds_read_b128 v[146:149], v0 offset:3072
	ds_read_b128 v[142:145], v221 offset:8192
	ds_read_b128 v[150:153], v221 offset:9216
	ds_read_b128 v[154:157], v221 offset:10240
	ds_read_b128 v[158:161], v221 offset:11264
	ds_read_b128 v[162:165], v221 offset:12288
	ds_read_b128 v[166:169], v221 offset:13312
	ds_read_b128 v[170:173], v221 offset:14336
	ds_read_b128 v[174:177], v221 offset:15360
	s_waitcnt lgkmcnt(7)
	v_mfma_f32_16x16x32_bf16 v[126:129], v[142:145], v[130:133], v[126:129]
	v_mfma_f32_16x16x32_bf16 v[122:125], v[142:145], v[134:137], v[122:125]
	v_mfma_f32_16x16x32_bf16 v[118:121], v[142:145], v[138:141], v[118:121]
	v_mfma_f32_16x16x32_bf16 v[114:117], v[142:145], v[146:149], v[114:117]
	s_waitcnt lgkmcnt(6)
	v_mfma_f32_16x16x32_bf16 v[110:113], v[150:153], v[130:133], v[110:113]
	v_mfma_f32_16x16x32_bf16 v[106:109], v[150:153], v[134:137], v[106:109]
	v_mfma_f32_16x16x32_bf16 v[102:105], v[150:153], v[138:141], v[102:105]
	v_mfma_f32_16x16x32_bf16 v[98:101], v[150:153], v[146:149], v[98:101]
	s_waitcnt lgkmcnt(5)
	v_mfma_f32_16x16x32_bf16 v[94:97], v[154:157], v[130:133], v[94:97]
	v_mfma_f32_16x16x32_bf16 v[90:93], v[154:157], v[134:137], v[90:93]
	v_mfma_f32_16x16x32_bf16 v[86:89], v[154:157], v[138:141], v[86:89]
	v_mfma_f32_16x16x32_bf16 v[82:85], v[154:157], v[146:149], v[82:85]
	s_waitcnt lgkmcnt(4)
	v_mfma_f32_16x16x32_bf16 v[78:81], v[158:161], v[130:133], v[78:81]
	v_mfma_f32_16x16x32_bf16 v[74:77], v[158:161], v[134:137], v[74:77]
	v_mfma_f32_16x16x32_bf16 v[70:73], v[158:161], v[138:141], v[70:73]
	v_mfma_f32_16x16x32_bf16 v[66:69], v[158:161], v[146:149], v[66:69]
	s_waitcnt lgkmcnt(3)
	v_mfma_f32_16x16x32_bf16 v[142:145], v[162:165], v[130:133], v[62:65]
	v_mfma_f32_16x16x32_bf16 v[150:153], v[162:165], v[134:137], v[58:61]
	v_mfma_f32_16x16x32_bf16 v[154:157], v[162:165], v[138:141], v[54:57]
	v_mfma_f32_16x16x32_bf16 v[158:161], v[162:165], v[146:149], v[50:53]
	s_waitcnt lgkmcnt(2)
	v_mfma_f32_16x16x32_bf16 v[162:165], v[166:169], v[130:133], v[46:49]
	v_mfma_f32_16x16x32_bf16 v[178:181], v[166:169], v[134:137], v[42:45]
	v_mfma_f32_16x16x32_bf16 v[182:185], v[166:169], v[138:141], v[38:41]
	v_mfma_f32_16x16x32_bf16 v[166:169], v[166:169], v[146:149], v[34:37]
	s_waitcnt lgkmcnt(1)
	v_mfma_f32_16x16x32_bf16 v[186:189], v[170:173], v[130:133], v[30:33]
	v_mfma_f32_16x16x32_bf16 v[190:193], v[170:173], v[134:137], v[26:29]
	v_mfma_f32_16x16x32_bf16 v[194:197], v[170:173], v[138:141], v[22:25]
	v_mfma_f32_16x16x32_bf16 v[170:173], v[170:173], v[146:149], v[18:21]
	s_waitcnt lgkmcnt(0)
	v_mfma_f32_16x16x32_bf16 v[130:133], v[174:177], v[130:133], v[14:17]
	v_mfma_f32_16x16x32_bf16 v[134:137], v[174:177], v[134:137], v[10:13]
	v_mfma_f32_16x16x32_bf16 v[138:141], v[174:177], v[138:141], v[6:9]
	v_mfma_f32_16x16x32_bf16 v[146:149], v[174:177], v[146:149], v[2:5]
	s_waitcnt vmcnt(0)
	s_waitcnt lgkmcnt(0)
	s_barrier
	ds_read_b128 v[174:177], v0 offset:24576
	ds_read_b128 v[198:201], v0 offset:25600
	ds_read_b128 v[202:205], v0 offset:26624
	ds_read_b128 v[206:209], v0 offset:27648
	ds_read_b128 v[14:17], v221 offset:32768
	ds_read_b128 v[30:33], v221 offset:33792
	ds_read_b128 v[46:49], v221 offset:34816
	ds_read_b128 v[62:65], v221 offset:35840
	ds_read_b128 v[210:213], v221 offset:36864
	ds_read_b128 v[216:219], v221 offset:37888
	ds_read_b128 v[226:229], v221 offset:38912
	ds_read_b128 v[230:233], v221 offset:39936
	s_waitcnt lgkmcnt(7)
	v_mfma_f32_16x16x32_bf16 v[2:5], v[14:17], v[174:177], v[126:129]
	v_mfma_f32_16x16x32_bf16 v[6:9], v[14:17], v[198:201], v[122:125]
	v_mfma_f32_16x16x32_bf16 v[10:13], v[14:17], v[202:205], v[118:121]
	v_mfma_f32_16x16x32_bf16 v[14:17], v[14:17], v[206:209], v[114:117]
	s_waitcnt lgkmcnt(6)
	v_mfma_f32_16x16x32_bf16 v[18:21], v[30:33], v[174:177], v[110:113]
	v_mfma_f32_16x16x32_bf16 v[22:25], v[30:33], v[198:201], v[106:109]
	v_mfma_f32_16x16x32_bf16 v[26:29], v[30:33], v[202:205], v[102:105]
	v_mfma_f32_16x16x32_bf16 v[30:33], v[30:33], v[206:209], v[98:101]
	s_waitcnt lgkmcnt(5)
	v_mfma_f32_16x16x32_bf16 v[34:37], v[46:49], v[174:177], v[94:97]
	v_mfma_f32_16x16x32_bf16 v[38:41], v[46:49], v[198:201], v[90:93]
	v_mfma_f32_16x16x32_bf16 v[42:45], v[46:49], v[202:205], v[86:89]
	v_mfma_f32_16x16x32_bf16 v[46:49], v[46:49], v[206:209], v[82:85]
	s_waitcnt lgkmcnt(4)
	v_mfma_f32_16x16x32_bf16 v[50:53], v[62:65], v[174:177], v[78:81]
	v_mfma_f32_16x16x32_bf16 v[54:57], v[62:65], v[198:201], v[74:77]
	v_mfma_f32_16x16x32_bf16 v[58:61], v[62:65], v[202:205], v[70:73]
	v_mfma_f32_16x16x32_bf16 v[62:65], v[62:65], v[206:209], v[66:69]
	s_waitcnt lgkmcnt(3)
	v_mfma_f32_16x16x32_bf16 v[66:69], v[210:213], v[174:177], v[142:145]
	v_mfma_f32_16x16x32_bf16 v[70:73], v[210:213], v[198:201], v[150:153]
	v_mfma_f32_16x16x32_bf16 v[74:77], v[210:213], v[202:205], v[154:157]
	v_mfma_f32_16x16x32_bf16 v[78:81], v[210:213], v[206:209], v[158:161]
	s_waitcnt lgkmcnt(2)
	v_mfma_f32_16x16x32_bf16 v[82:85], v[216:219], v[174:177], v[162:165]
	v_mfma_f32_16x16x32_bf16 v[86:89], v[216:219], v[198:201], v[178:181]
	v_mfma_f32_16x16x32_bf16 v[90:93], v[216:219], v[202:205], v[182:185]
	v_mfma_f32_16x16x32_bf16 v[94:97], v[216:219], v[206:209], v[166:169]
	s_waitcnt lgkmcnt(1)
	v_mfma_f32_16x16x32_bf16 v[98:101], v[226:229], v[174:177], v[186:189]
	v_mfma_f32_16x16x32_bf16 v[102:105], v[226:229], v[198:201], v[190:193]
	v_mfma_f32_16x16x32_bf16 v[106:109], v[226:229], v[202:205], v[194:197]
	v_mfma_f32_16x16x32_bf16 v[110:113], v[226:229], v[206:209], v[170:173]
	s_waitcnt lgkmcnt(0)
	v_mfma_f32_16x16x32_bf16 v[114:117], v[230:233], v[174:177], v[130:133]
	v_mfma_f32_16x16x32_bf16 v[118:121], v[230:233], v[198:201], v[134:137]
	v_mfma_f32_16x16x32_bf16 v[122:125], v[230:233], v[202:205], v[138:141]
	v_mfma_f32_16x16x32_bf16 v[126:129], v[230:233], v[206:209], v[146:149]
	v_mov_b32_e32 v130, v224
	s_ashr_i32 s13, s12, 31
	v_and_b32_e32 v131, 31, v130
	v_ashrrev_i32_e32 v197, 7, v130
	v_ashrrev_i32_e32 v132, 5, v130
	v_lshlrev_b32_e32 v0, 2, v131
	s_lshl_b64 s[68:69], s[12:13], 11
	v_lshlrev_b32_e32 v164, 4, v131
	v_cmp_eq_u32_e64 s[42:43], 0, v131
	v_and_b32_e32 v131, 0x4f, v130
	v_and_b32_e32 v130, 48, v130
	s_movk_i32 s13, 0x210
	v_cmp_lt_i32_e32 vcc, v247, v214
	v_mad_u32_u24 v202, v131, s13, v130
	s_ashr_i32 s1, s0, 31
	v_cndmask_b32_e32 v130, v225, v247, vcc
	v_cmp_lt_i32_e32 vcc, v248, v214
	v_lshlrev_b32_e32 v203, 2, v130
	s_lshl_b32 s70, s87, 1
	v_cndmask_b32_e32 v130, v225, v248, vcc
	v_cmp_lt_i32_e32 vcc, v249, v214
	v_lshlrev_b32_e32 v204, 2, v130
	v_lshl_or_b32 v0, v132, 10, v0
	v_cndmask_b32_e32 v130, v225, v249, vcc
	v_cmp_lt_i32_e32 vcc, v223, v214
	v_lshlrev_b32_e32 v205, 2, v130
	v_mul_lo_u32 v165, v132, s13
	v_cndmask_b32_e32 v130, v225, v223, vcc
	v_cmp_lt_i32_e32 vcc, v252, v214
	v_lshlrev_b32_e32 v206, 2, v130
	s_mov_b32 s14, 0
	v_cndmask_b32_e32 v130, v225, v252, vcc
	v_lshlrev_b32_e32 v207, 2, v130
	v_add_u32_e32 v130, s12, v132
	v_ashrrev_i32_e32 v131, 31, v130
	s_add_u32 s12, s74, s68
	v_lshlrev_b64 v[132:133], 5, v[130:131]
	v_add_u32_e32 v134, 8, v130
	v_add_u32_e32 v136, 16, v130
	v_add_u32_e32 v138, 24, v130
	v_add_u32_e32 v140, 32, v130
	v_add_u32_e32 v142, 40, v130
	v_add_u32_e32 v144, 48, v130
	v_add_u32_e32 v146, 56, v130
	v_add_u32_e32 v148, 64, v130
	v_add_u32_e32 v150, 0x48, v130
	v_add_u32_e32 v152, 0x50, v130
	v_add_u32_e32 v154, 0x58, v130
	v_add_u32_e32 v156, 0x60, v130
	v_add_u32_e32 v158, 0x68, v130
	v_add_u32_e32 v160, 0x70, v130
	v_add_u32_e32 v130, 0x78, v130
	s_addc_u32 s13, s75, s69
	s_lshl_b64 s[0:1], s[0:1], 1
	v_ashrrev_i32_e32 v135, 31, v134
	v_ashrrev_i32_e32 v137, 31, v136
	v_ashrrev_i32_e32 v139, 31, v138
	v_ashrrev_i32_e32 v141, 31, v140
	v_ashrrev_i32_e32 v143, 31, v142
	v_ashrrev_i32_e32 v145, 31, v144
	v_ashrrev_i32_e32 v147, 31, v146
	v_ashrrev_i32_e32 v149, 31, v148
	v_ashrrev_i32_e32 v151, 31, v150
	v_ashrrev_i32_e32 v153, 31, v152
	v_ashrrev_i32_e32 v155, 31, v154
	v_ashrrev_i32_e32 v157, 31, v156
	v_ashrrev_i32_e32 v159, 31, v158
	v_ashrrev_i32_e32 v161, 31, v160
	v_ashrrev_i32_e32 v131, 31, v130
	s_add_u32 s0, s12, s0
	v_lshlrev_b64 v[134:135], 5, v[134:135]
	v_lshlrev_b64 v[136:137], 5, v[136:137]
	v_lshlrev_b64 v[138:139], 5, v[138:139]
	v_lshlrev_b64 v[140:141], 5, v[140:141]
	v_lshlrev_b64 v[142:143], 5, v[142:143]
	v_lshlrev_b64 v[144:145], 5, v[144:145]
	v_lshlrev_b64 v[146:147], 5, v[146:147]
	v_lshlrev_b64 v[148:149], 5, v[148:149]
	v_lshlrev_b64 v[150:151], 5, v[150:151]
	v_lshlrev_b64 v[152:153], 5, v[152:153]
	v_lshlrev_b64 v[154:155], 5, v[154:155]
	v_lshlrev_b64 v[156:157], 5, v[156:157]
	v_lshlrev_b64 v[158:159], 5, v[158:159]
	v_lshlrev_b64 v[160:161], 5, v[160:161]
	v_lshlrev_b64 v[162:163], 5, v[130:131]
	s_addc_u32 s1, s13, s1
	v_lshl_add_u64 v[130:131], v[0:1], 1, s[0:1]
	v_lshl_add_u64 v[132:133], s[44:45], 0, v[132:133]
	v_lshl_add_u64 v[134:135], s[44:45], 0, v[134:135]
	v_lshl_add_u64 v[136:137], s[44:45], 0, v[136:137]
	v_lshl_add_u64 v[138:139], s[44:45], 0, v[138:139]
	v_lshl_add_u64 v[140:141], s[44:45], 0, v[140:141]
	v_lshl_add_u64 v[142:143], s[44:45], 0, v[142:143]
	v_lshl_add_u64 v[144:145], s[44:45], 0, v[144:145]
	v_lshl_add_u64 v[146:147], s[44:45], 0, v[146:147]
	v_lshl_add_u64 v[148:149], s[44:45], 0, v[148:149]
	v_lshl_add_u64 v[150:151], s[44:45], 0, v[150:151]
	v_lshl_add_u64 v[152:153], s[44:45], 0, v[152:153]
	v_lshl_add_u64 v[154:155], s[44:45], 0, v[154:155]
	v_lshl_add_u64 v[156:157], s[44:45], 0, v[156:157]
	v_lshl_add_u64 v[158:159], s[44:45], 0, v[158:159]
	v_lshl_add_u64 v[160:161], s[44:45], 0, v[160:161]
	v_lshl_add_u64 v[162:163], s[44:45], 0, v[162:163]
	s_mov_b64 s[0:1], -1
	v_add_u32_e32 v0, v164, v165
	s_branch .LBB0_122

.LBB0_193:
	s_waitcnt vmcnt(1)
	v_mov_b32_e32 v16, v224
	s_lshl_b32 s46, s57, 8
	v_readfirstlane_b32 s40, v16
	s_and_b32 s14, s40, 0xffffffc0
	v_bfe_u32 v17, v16, 4, 2
	v_bfe_u32 v12, v16, 2, 4
	s_add_i32 s14, s14, s46
	v_sub_u32_e32 v18, 0, v17
	v_or_b32_e32 v10, s14, v12
	s_lshl_b32 s12, s68, 7
	s_ashr_i32 s41, s40, 6
	v_xor_b32_e32 v0, v16, v18
	v_min_i32_e32 v4, 0x3ff, v10
	v_or_b32_e32 v6, 16, v10
	v_or_b32_e32 v8, 32, v10
	v_or_b32_e32 v10, 48, v10
	v_lshlrev_b32_e32 v0, 4, v0
	v_min_i32_e32 v6, 0x3ff, v6
	v_min_i32_e32 v8, 0x3ff, v8
	v_min_i32_e32 v10, 0x3ff, v10
	s_lshl_b32 s14, s41, 1
	v_or_b32_e32 v14, s12, v12
	v_and_b32_e32 v0, 48, v0
	v_ashrrev_i32_e32 v5, 31, v4
	v_ashrrev_i32_e32 v7, 31, v6
	v_ashrrev_i32_e32 v9, 31, v8
	v_ashrrev_i32_e32 v11, 31, v10
	v_lshl_add_u32 v12, s41, 5, v14
	s_lshl_b32 s47, s14, 10
	s_or_b32 s14, s14, 1
	v_lshl_add_u64 v[2:3], s[4:5], 0, v[0:1]
	v_lshlrev_b64 v[4:5], 6, v[4:5]
	v_lshlrev_b64 v[6:7], 6, v[6:7]
	v_lshlrev_b64 v[8:9], 6, v[8:9]
	v_lshlrev_b64 v[10:11], 6, v[10:11]
	v_ashrrev_i32_e32 v13, 31, v12
	v_lshl_add_u32 v14, s14, 4, v14
	v_lshl_add_u64 v[4:5], v[2:3], 0, v[4:5]
	v_lshl_add_u64 v[6:7], v[2:3], 0, v[6:7]
	v_lshl_add_u64 v[8:9], v[2:3], 0, v[8:9]
	v_lshl_add_u64 v[2:3], v[2:3], 0, v[10:11]
	v_lshl_add_u64 v[10:11], s[0:1], 0, v[0:1]
	v_lshlrev_b64 v[130:131], 10, v[12:13]
	v_lshlrev_b64 v[12:13], 11, v[12:13]
	v_ashrrev_i32_e32 v15, 31, v14
	s_waitcnt vmcnt(0)
	s_waitcnt lgkmcnt(0)
	s_barrier
	v_lshl_add_u64 v[12:13], v[10:11], 0, v[12:13]
	s_mov_b32 s15, m0
	s_mov_b32 m0, s47
	s_nop 0
	global_load_lds_dwordx4 v[12:13], off
	s_mov_b32 m0, s15
	v_lshlrev_b64 v[132:133], 10, v[14:15]
	v_lshlrev_b64 v[14:15], 11, v[14:15]
	v_lshl_add_u64 v[10:11], v[10:11], 0, v[14:15]
	s_lshl_b32 s14, s14, 10
	s_mov_b32 s15, m0
	s_mov_b32 m0, s14
	s_nop 0
	global_load_lds_dwordx4 v[10:11], off
	s_mov_b32 m0, s15
	s_lshl_b32 s48, s41, 12
	s_add_i32 s15, s48, 0x2000
	s_mov_b32 s49, m0
	s_mov_b32 m0, s15
	s_nop 0
	global_load_lds_dwordx4 v[4:5], off
	s_mov_b32 m0, s49
	s_add_i32 s49, s48, 0x2400
	s_mov_b32 s69, m0
	s_mov_b32 m0, s49
	s_nop 0
	global_load_lds_dwordx4 v[6:7], off
	s_mov_b32 m0, s69
	s_add_i32 s49, s48, 0x2800
	s_mov_b32 s69, m0
	s_mov_b32 m0, s49
	s_nop 0
	global_load_lds_dwordx4 v[8:9], off
	s_mov_b32 m0, s69
	s_add_i32 s49, s48, 0x2c00
	s_mov_b32 s69, m0
	s_mov_b32 m0, s49
	s_nop 0
	global_load_lds_dwordx4 v[2:3], off
	s_mov_b32 m0, s69
	v_lshl_add_u64 v[12:13], v[12:13], 0, 64
	s_addk_i32 s47, 0x6000
	s_mov_b32 s49, m0
	s_mov_b32 m0, s47
	s_nop 0
	global_load_lds_dwordx4 v[12:13], off
	s_mov_b32 m0, s49
	v_lshl_add_u64 v[10:11], v[10:11], 0, 64
	s_add_i32 s47, s14, 0x6000
	s_mov_b32 s49, m0
	s_mov_b32 m0, s47
	s_nop 0
	global_load_lds_dwordx4 v[10:11], off
	s_mov_b32 m0, s49
	s_mov_b32 s100, 0x10000
	s_mov_b32 s101, 0
	v_lshl_add_u64 v[10:11], v[4:5], 0, s[100:101]
	v_lshrrev_b32_e32 v0, 2, v16
	s_add_i32 s47, s48, 0x8000
	s_mov_b32 s49, m0
	s_mov_b32 m0, s47
	s_nop 0
	global_load_lds_dwordx4 v[10:11], off
	s_mov_b32 m0, s49
	v_lshl_add_u64 v[10:11], v[6:7], 0, s[100:101]
	v_sub_u32_e32 v0, 0, v0
	s_add_i32 s47, s48, 0x8400
	s_mov_b32 s49, m0
	s_mov_b32 m0, s47
	s_nop 0
	global_load_lds_dwordx4 v[10:11], off
	s_mov_b32 m0, s49
	v_lshl_add_u64 v[10:11], v[8:9], 0, s[100:101]
	v_bitop3_b32 v0, v17, v0, 3 bitop3:0x78
	s_add_i32 s47, s48, 0x8800
	s_mov_b32 s49, m0
	s_mov_b32 m0, s47
	s_nop 0
	global_load_lds_dwordx4 v[10:11], off
	s_mov_b32 m0, s49
	v_lshl_add_u64 v[10:11], v[2:3], 0, s[100:101]
	v_lshlrev_b32_e32 v144, 4, v0
	v_and_b32_e32 v0, 15, v16
	s_add_i32 s48, s48, 0x8c00
	s_mov_b32 s47, m0
	s_mov_b32 m0, s48
	s_nop 0
	global_load_lds_dwordx4 v[10:11], off
	s_mov_b32 m0, s47
	v_and_or_b32 v10, s40, 64, v0
	s_and_b32 s40, s40, 0x3ffff80
	v_or_b32_e32 v0, s40, v0
	v_lshlrev_b32_e32 v145, 6, v0
	v_bitop3_b32 v0, v16, 3, v18 bitop3:0x48
	s_mov_b32 s100, 0x20000
	v_lshl_add_u64 v[134:135], v[2:3], 0, s[100:101]
	v_lshlrev_b32_e32 v0, 4, v0
	v_mov_b32_e32 v2, 0
	s_mov_b32 s13, 0
	v_lshlrev_b32_e32 v146, 6, v10
	s_lshl_b32 s47, s41, 11
	v_lshl_add_u64 v[136:137], v[8:9], 0, s[100:101]
	v_lshl_add_u64 v[138:139], v[6:7], 0, s[100:101]
	v_lshl_add_u64 v[140:141], v[4:5], 0, s[100:101]
	v_lshl_add_u64 v[142:143], s[44:45], 0, v[0:1]
	s_mov_b64 s[40:41], 0
	v_mov_b32_e32 v3, v2
	v_mov_b32_e32 v4, v2
	v_mov_b32_e32 v5, v2
	v_mov_b32_e32 v6, v2
	v_mov_b32_e32 v7, v2
	v_mov_b32_e32 v8, v2
	v_mov_b32_e32 v9, v2
	v_mov_b32_e32 v10, v2
	v_mov_b32_e32 v11, v2
	v_mov_b32_e32 v12, v2
	v_mov_b32_e32 v13, v2
	v_mov_b32_e32 v14, v2
	v_mov_b32_e32 v15, v2
	v_mov_b32_e32 v16, v2
	v_mov_b32_e32 v17, v2
	v_mov_b32_e32 v18, v2
	v_mov_b32_e32 v19, v2
	v_mov_b32_e32 v20, v2
	v_mov_b32_e32 v21, v2
	v_mov_b32_e32 v22, v2
	v_mov_b32_e32 v23, v2
	v_mov_b32_e32 v24, v2
	v_mov_b32_e32 v25, v2
	v_mov_b32_e32 v26, v2
	v_mov_b32_e32 v27, v2
	v_mov_b32_e32 v28, v2
	v_mov_b32_e32 v29, v2
	v_mov_b32_e32 v30, v2
	v_mov_b32_e32 v31, v2
	v_mov_b32_e32 v32, v2
	v_mov_b32_e32 v33, v2
	v_mov_b32_e32 v34, v2
	v_mov_b32_e32 v35, v2
	v_mov_b32_e32 v36, v2
	v_mov_b32_e32 v37, v2
	v_mov_b32_e32 v38, v2
	v_mov_b32_e32 v39, v2
	v_mov_b32_e32 v40, v2
	v_mov_b32_e32 v41, v2
	v_mov_b32_e32 v42, v2
	v_mov_b32_e32 v43, v2
	v_mov_b32_e32 v44, v2
	v_mov_b32_e32 v45, v2
	s_waitcnt vmcnt(0)
	v_mov_b32_e32 v46, v2
	v_mov_b32_e32 v47, v2
	v_mov_b32_e32 v48, v2
	v_mov_b32_e32 v49, v2
	v_mov_b32_e32 v50, v2
	v_mov_b32_e32 v51, v2
	v_mov_b32_e32 v52, v2
	v_mov_b32_e32 v53, v2
	v_mov_b32_e32 v54, v2
	v_mov_b32_e32 v55, v2
	v_mov_b32_e32 v56, v2
	v_mov_b32_e32 v57, v2
	v_mov_b32_e32 v58, v2
	v_mov_b32_e32 v59, v2
	v_mov_b32_e32 v60, v2
	v_mov_b32_e32 v61, v2
	v_mov_b32_e32 v62, v2
	v_mov_b32_e32 v63, v2
	v_mov_b32_e32 v64, v2
	v_mov_b32_e32 v65, v2
	v_mov_b32_e32 v66, v2
	v_mov_b32_e32 v67, v2
	v_mov_b32_e32 v68, v2
	v_mov_b32_e32 v69, v2
	v_mov_b32_e32 v70, v2
	v_mov_b32_e32 v71, v2
	v_mov_b32_e32 v72, v2
	v_mov_b32_e32 v73, v2
	v_mov_b32_e32 v74, v2
	v_mov_b32_e32 v75, v2
	v_mov_b32_e32 v76, v2
	v_mov_b32_e32 v77, v2
	v_mov_b32_e32 v78, v2
	v_mov_b32_e32 v79, v2
	v_mov_b32_e32 v80, v2
	v_mov_b32_e32 v81, v2
	v_mov_b32_e32 v82, v2
	v_mov_b32_e32 v83, v2
	v_mov_b32_e32 v84, v2
	v_mov_b32_e32 v85, v2
	v_mov_b32_e32 v86, v2
	v_mov_b32_e32 v87, v2
	v_mov_b32_e32 v88, v2
	v_mov_b32_e32 v89, v2
	v_mov_b32_e32 v90, v2
	v_mov_b32_e32 v91, v2
	v_mov_b32_e32 v92, v2
	v_mov_b32_e32 v93, v2
	v_mov_b32_e32 v94, v2
	v_mov_b32_e32 v95, v2
	v_mov_b32_e32 v96, v2
	v_mov_b32_e32 v97, v2
	v_mov_b32_e32 v98, v2
	v_mov_b32_e32 v99, v2
	v_mov_b32_e32 v100, v2
	v_mov_b32_e32 v101, v2
	v_mov_b32_e32 v102, v2
	v_mov_b32_e32 v103, v2
	v_mov_b32_e32 v104, v2
	v_mov_b32_e32 v105, v2
	v_mov_b32_e32 v106, v2
	v_mov_b32_e32 v107, v2
	v_mov_b32_e32 v108, v2
	v_mov_b32_e32 v109, v2
	v_mov_b32_e32 v110, v2
	v_mov_b32_e32 v111, v2
	v_mov_b32_e32 v112, v2
	v_mov_b32_e32 v113, v2
	v_mov_b32_e32 v114, v2
	v_mov_b32_e32 v115, v2
	v_mov_b32_e32 v116, v2
	v_mov_b32_e32 v117, v2
	v_mov_b32_e32 v118, v2
	v_mov_b32_e32 v119, v2
	v_mov_b32_e32 v120, v2
	v_mov_b32_e32 v121, v2
	v_mov_b32_e32 v122, v2
	v_mov_b32_e32 v123, v2
	v_mov_b32_e32 v124, v2
	v_mov_b32_e32 v125, v2
	v_mov_b32_e32 v126, v2
	v_mov_b32_e32 v127, v2
	v_mov_b32_e32 v128, v2
	v_mov_b32_e32 v129, v2
.LBB0_194:
	s_mul_i32 s100, s40, 0x400
	s_mul_i32 s48, s13, 0x6000
	s_add_i32 s49, s48, 0xffffa000
	s_cmp_gt_i32 s13, 0
	s_waitcnt vmcnt(6)
	s_cselect_b32 s49, s49, 0xc000
	s_waitcnt lgkmcnt(0)
	s_barrier
	s_setprio 2
	v_or_b32_e32 v0, s48, v146
	v_add_u32_e32 v0, v0, v144
	v_add3_u32 v212, s48, v145, v144
	ds_read_b128 v[164:167], v212 offset:8192
	ds_read_b128 v[148:151], v0
	ds_read_b128 v[152:155], v0 offset:1024
	ds_read_b128 v[156:159], v0 offset:2048
	ds_read_b128 v[160:163], v0 offset:3072
	ds_read_b128 v[168:171], v212 offset:9216
	ds_read_b128 v[172:175], v212 offset:10240
	ds_read_b128 v[176:179], v212 offset:11264
	ds_read_b128 v[180:183], v212 offset:12288
	ds_read_b128 v[184:187], v212 offset:13312
	ds_read_b128 v[188:191], v212 offset:14336
	ds_read_b128 v[198:201], v212 offset:15360
	v_lshl_add_u64 v[212:213], v[142:143], 0, s[40:41]
	v_lshl_add_u64 v[212:213], v[130:131], 1, v[212:213]
	s_add_i32 s69, s49, s47
	s_mov_b32 m0, s69
	s_nop 0
	global_load_lds_dwordx4 v[212:213], off
	v_lshl_add_u64 v[212:213], v[142:143], 0, s[40:41]
	v_lshl_add_u64 v[212:213], v[132:133], 1, v[212:213]
	s_add_i32 s69, s49, s14
	s_mov_b32 m0, s69
	s_nop 0
	global_load_lds_dwordx4 v[212:213], off
	s_add_i32 s49, s15, s49
	v_lshl_add_u64 v[212:213], v[140:141], 0, s[100:101]
	s_mov_b32 m0, s49
	s_nop 0
	global_load_lds_dwordx4 v[212:213], off
	v_lshl_add_u64 v[212:213], v[138:139], 0, s[100:101]
	s_add_i32 s69, s49, 0x400
	s_mov_b32 m0, s69
	s_nop 0
	global_load_lds_dwordx4 v[212:213], off
	v_lshl_add_u64 v[212:213], v[136:137], 0, s[100:101]
	s_add_i32 s69, s49, 0x800
	s_mov_b32 m0, s69
	s_nop 0
	global_load_lds_dwordx4 v[212:213], off
	v_lshl_add_u64 v[212:213], v[134:135], 0, s[100:101]
	s_addk_i32 s49, 0xc00
	s_mov_b32 m0, s49
	s_nop 0
	global_load_lds_dwordx4 v[212:213], off
	s_setprio 0
	s_waitcnt lgkmcnt(10)
	v_mfma_f32_16x16x32_bf16 v[126:129], v[164:167], v[148:151], v[126:129]
	s_waitcnt lgkmcnt(9)
	v_mfma_f32_16x16x32_bf16 v[122:125], v[164:167], v[152:155], v[122:125]
	s_waitcnt lgkmcnt(8)
	v_mfma_f32_16x16x32_bf16 v[118:121], v[164:167], v[156:159], v[118:121]
	s_waitcnt lgkmcnt(7)
	v_mfma_f32_16x16x32_bf16 v[114:117], v[164:167], v[160:163], v[114:117]
	s_waitcnt lgkmcnt(6)
	v_mfma_f32_16x16x32_bf16 v[110:113], v[168:171], v[148:151], v[110:113]
	v_mfma_f32_16x16x32_bf16 v[106:109], v[168:171], v[152:155], v[106:109]
	v_mfma_f32_16x16x32_bf16 v[102:105], v[168:171], v[156:159], v[102:105]
	v_mfma_f32_16x16x32_bf16 v[98:101], v[168:171], v[160:163], v[98:101]
	s_waitcnt lgkmcnt(5)
	v_mfma_f32_16x16x32_bf16 v[94:97], v[172:175], v[148:151], v[94:97]
	v_mfma_f32_16x16x32_bf16 v[90:93], v[172:175], v[152:155], v[90:93]
	v_mfma_f32_16x16x32_bf16 v[86:89], v[172:175], v[156:159], v[86:89]
	v_mfma_f32_16x16x32_bf16 v[82:85], v[172:175], v[160:163], v[82:85]
	s_waitcnt lgkmcnt(4)
	v_mfma_f32_16x16x32_bf16 v[78:81], v[176:179], v[148:151], v[78:81]
	v_mfma_f32_16x16x32_bf16 v[74:77], v[176:179], v[152:155], v[74:77]
	v_mfma_f32_16x16x32_bf16 v[70:73], v[176:179], v[156:159], v[70:73]
	v_mfma_f32_16x16x32_bf16 v[66:69], v[176:179], v[160:163], v[66:69]
	s_waitcnt lgkmcnt(3)
	v_mfma_f32_16x16x32_bf16 v[62:65], v[180:183], v[148:151], v[62:65]
	v_mfma_f32_16x16x32_bf16 v[58:61], v[180:183], v[152:155], v[58:61]
	v_mfma_f32_16x16x32_bf16 v[54:57], v[180:183], v[156:159], v[54:57]
	v_mfma_f32_16x16x32_bf16 v[50:53], v[180:183], v[160:163], v[50:53]
	s_waitcnt lgkmcnt(2)
	v_mfma_f32_16x16x32_bf16 v[46:49], v[184:187], v[148:151], v[46:49]
	v_mfma_f32_16x16x32_bf16 v[42:45], v[184:187], v[152:155], v[42:45]
	v_mfma_f32_16x16x32_bf16 v[38:41], v[184:187], v[156:159], v[38:41]
	v_mfma_f32_16x16x32_bf16 v[34:37], v[184:187], v[160:163], v[34:37]
	s_waitcnt lgkmcnt(1)
	v_mfma_f32_16x16x32_bf16 v[30:33], v[188:191], v[148:151], v[30:33]
	v_mfma_f32_16x16x32_bf16 v[26:29], v[188:191], v[152:155], v[26:29]
	v_mfma_f32_16x16x32_bf16 v[22:25], v[188:191], v[156:159], v[22:25]
	v_mfma_f32_16x16x32_bf16 v[18:21], v[188:191], v[160:163], v[18:21]
	s_waitcnt lgkmcnt(0)
	v_mfma_f32_16x16x32_bf16 v[14:17], v[198:201], v[148:151], v[14:17]
	v_mfma_f32_16x16x32_bf16 v[10:13], v[198:201], v[152:155], v[10:13]
	v_mfma_f32_16x16x32_bf16 v[6:9], v[198:201], v[156:159], v[6:9]
	v_mfma_f32_16x16x32_bf16 v[2:5], v[198:201], v[160:163], v[2:5]
	s_add_i32 s48, s13, 1
	s_cmp_lg_u32 s13, 2
	s_cselect_b32 s13, s48, 0
	s_add_u32 s40, s40, 64
	s_addc_u32 s41, s41, 0
	s_cmpk_eq_i32 s40, 0x780
	s_cbranch_scc0 .LBB0_194
	s_waitcnt vmcnt(6)
	v_add_u32_e32 v0, v146, v144
	v_add_u32_e32 v194, v145, v144
	s_waitcnt lgkmcnt(0)
	s_barrier
	ds_read_b128 v[130:133], v0
	ds_read_b128 v[134:137], v0 offset:1024
	ds_read_b128 v[138:141], v0 offset:2048
	ds_read_b128 v[146:149], v0 offset:3072
	ds_read_b128 v[142:145], v194 offset:8192
	ds_read_b128 v[150:153], v194 offset:9216
	ds_read_b128 v[154:157], v194 offset:10240
	ds_read_b128 v[158:161], v194 offset:11264
	ds_read_b128 v[162:165], v194 offset:12288
	ds_read_b128 v[166:169], v194 offset:13312
	ds_read_b128 v[170:173], v194 offset:14336
	ds_read_b128 v[174:177], v194 offset:15360
	s_waitcnt lgkmcnt(7)
	v_mfma_f32_16x16x32_bf16 v[126:129], v[142:145], v[130:133], v[126:129]
	v_mfma_f32_16x16x32_bf16 v[122:125], v[142:145], v[134:137], v[122:125]
	v_mfma_f32_16x16x32_bf16 v[118:121], v[142:145], v[138:141], v[118:121]
	v_mfma_f32_16x16x32_bf16 v[114:117], v[142:145], v[146:149], v[114:117]
	s_waitcnt lgkmcnt(6)
	v_mfma_f32_16x16x32_bf16 v[110:113], v[150:153], v[130:133], v[110:113]
	v_mfma_f32_16x16x32_bf16 v[106:109], v[150:153], v[134:137], v[106:109]
	v_mfma_f32_16x16x32_bf16 v[102:105], v[150:153], v[138:141], v[102:105]
	v_mfma_f32_16x16x32_bf16 v[98:101], v[150:153], v[146:149], v[98:101]
	s_waitcnt lgkmcnt(5)
	v_mfma_f32_16x16x32_bf16 v[94:97], v[154:157], v[130:133], v[94:97]
	v_mfma_f32_16x16x32_bf16 v[90:93], v[154:157], v[134:137], v[90:93]
	v_mfma_f32_16x16x32_bf16 v[86:89], v[154:157], v[138:141], v[86:89]
	v_mfma_f32_16x16x32_bf16 v[82:85], v[154:157], v[146:149], v[82:85]
	s_waitcnt lgkmcnt(4)
	v_mfma_f32_16x16x32_bf16 v[78:81], v[158:161], v[130:133], v[78:81]
	v_mfma_f32_16x16x32_bf16 v[74:77], v[158:161], v[134:137], v[74:77]
	v_mfma_f32_16x16x32_bf16 v[70:73], v[158:161], v[138:141], v[70:73]
	v_mfma_f32_16x16x32_bf16 v[66:69], v[158:161], v[146:149], v[66:69]
	s_waitcnt lgkmcnt(3)
	v_mfma_f32_16x16x32_bf16 v[142:145], v[162:165], v[130:133], v[62:65]
	v_mfma_f32_16x16x32_bf16 v[150:153], v[162:165], v[134:137], v[58:61]
	v_mfma_f32_16x16x32_bf16 v[154:157], v[162:165], v[138:141], v[54:57]
	v_mfma_f32_16x16x32_bf16 v[158:161], v[162:165], v[146:149], v[50:53]
	s_waitcnt lgkmcnt(2)
	v_mfma_f32_16x16x32_bf16 v[162:165], v[166:169], v[130:133], v[46:49]
	v_mfma_f32_16x16x32_bf16 v[178:181], v[166:169], v[134:137], v[42:45]
	v_mfma_f32_16x16x32_bf16 v[182:185], v[166:169], v[138:141], v[38:41]
	v_mfma_f32_16x16x32_bf16 v[166:169], v[166:169], v[146:149], v[34:37]
	s_waitcnt lgkmcnt(1)
	v_mfma_f32_16x16x32_bf16 v[186:189], v[170:173], v[130:133], v[30:33]
	v_mfma_f32_16x16x32_bf16 v[190:193], v[170:173], v[134:137], v[26:29]
	v_mfma_f32_16x16x32_bf16 v[198:201], v[170:173], v[138:141], v[22:25]
	v_mfma_f32_16x16x32_bf16 v[170:173], v[170:173], v[146:149], v[18:21]
	s_waitcnt lgkmcnt(0)
	v_mfma_f32_16x16x32_bf16 v[130:133], v[174:177], v[130:133], v[14:17]
	v_mfma_f32_16x16x32_bf16 v[134:137], v[174:177], v[134:137], v[10:13]
	v_mfma_f32_16x16x32_bf16 v[138:141], v[174:177], v[138:141], v[6:9]
	v_mfma_f32_16x16x32_bf16 v[146:149], v[174:177], v[146:149], v[2:5]
	s_waitcnt vmcnt(0)
	s_waitcnt lgkmcnt(0)
	s_barrier
	ds_read_b128 v[174:177], v0 offset:24576
	ds_read_b128 v[202:205], v0 offset:25600
	ds_read_b128 v[216:219], v0 offset:26624
	ds_read_b128 v[226:229], v0 offset:27648
	ds_read_b128 v[14:17], v194 offset:32768
	ds_read_b128 v[30:33], v194 offset:33792
	ds_read_b128 v[46:49], v194 offset:34816
	ds_read_b128 v[62:65], v194 offset:35840
	ds_read_b128 v[230:233], v194 offset:36864
	ds_read_b128 v[234:237], v194 offset:37888
	ds_read_b128 v[238:241], v194 offset:38912
	ds_read_b128 v[242:245], v194 offset:39936
	s_waitcnt lgkmcnt(7)
	v_mfma_f32_16x16x32_bf16 v[2:5], v[14:17], v[174:177], v[126:129]
	v_mfma_f32_16x16x32_bf16 v[6:9], v[14:17], v[202:205], v[122:125]
	v_mfma_f32_16x16x32_bf16 v[10:13], v[14:17], v[216:219], v[118:121]
	v_mfma_f32_16x16x32_bf16 v[14:17], v[14:17], v[226:229], v[114:117]
	s_waitcnt lgkmcnt(6)
	v_mfma_f32_16x16x32_bf16 v[18:21], v[30:33], v[174:177], v[110:113]
	v_mfma_f32_16x16x32_bf16 v[22:25], v[30:33], v[202:205], v[106:109]
	v_mfma_f32_16x16x32_bf16 v[26:29], v[30:33], v[216:219], v[102:105]
	v_mfma_f32_16x16x32_bf16 v[30:33], v[30:33], v[226:229], v[98:101]
	s_waitcnt lgkmcnt(5)
	v_mfma_f32_16x16x32_bf16 v[34:37], v[46:49], v[174:177], v[94:97]
	v_mfma_f32_16x16x32_bf16 v[38:41], v[46:49], v[202:205], v[90:93]
	v_mfma_f32_16x16x32_bf16 v[42:45], v[46:49], v[216:219], v[86:89]
	v_mfma_f32_16x16x32_bf16 v[46:49], v[46:49], v[226:229], v[82:85]
	s_waitcnt lgkmcnt(4)
	v_mfma_f32_16x16x32_bf16 v[50:53], v[62:65], v[174:177], v[78:81]
	v_mfma_f32_16x16x32_bf16 v[54:57], v[62:65], v[202:205], v[74:77]
	v_mfma_f32_16x16x32_bf16 v[58:61], v[62:65], v[216:219], v[70:73]
	v_mfma_f32_16x16x32_bf16 v[62:65], v[62:65], v[226:229], v[66:69]
	s_waitcnt lgkmcnt(3)
	v_mfma_f32_16x16x32_bf16 v[66:69], v[230:233], v[174:177], v[142:145]
	v_mfma_f32_16x16x32_bf16 v[70:73], v[230:233], v[202:205], v[150:153]
	v_mfma_f32_16x16x32_bf16 v[74:77], v[230:233], v[216:219], v[154:157]
	v_mfma_f32_16x16x32_bf16 v[78:81], v[230:233], v[226:229], v[158:161]
	s_waitcnt lgkmcnt(2)
	v_mfma_f32_16x16x32_bf16 v[82:85], v[234:237], v[174:177], v[162:165]
	v_mfma_f32_16x16x32_bf16 v[86:89], v[234:237], v[202:205], v[178:181]
	v_mfma_f32_16x16x32_bf16 v[90:93], v[234:237], v[216:219], v[182:185]
	v_mfma_f32_16x16x32_bf16 v[94:97], v[234:237], v[226:229], v[166:169]
	s_waitcnt lgkmcnt(1)
	v_mfma_f32_16x16x32_bf16 v[98:101], v[238:241], v[174:177], v[186:189]
	v_mfma_f32_16x16x32_bf16 v[102:105], v[238:241], v[202:205], v[190:193]
	v_mfma_f32_16x16x32_bf16 v[106:109], v[238:241], v[216:219], v[198:201]
	v_mfma_f32_16x16x32_bf16 v[110:113], v[238:241], v[226:229], v[170:173]
	s_waitcnt lgkmcnt(0)
	v_mfma_f32_16x16x32_bf16 v[114:117], v[242:245], v[174:177], v[130:133]
	v_mfma_f32_16x16x32_bf16 v[118:121], v[242:245], v[202:205], v[134:137]
	v_mfma_f32_16x16x32_bf16 v[122:125], v[242:245], v[216:219], v[138:141]
	v_mfma_f32_16x16x32_bf16 v[126:129], v[242:245], v[226:229], v[146:149]
	v_mov_b32_e32 v130, v224
	s_ashr_i32 s13, s12, 31
	v_and_b32_e32 v131, 31, v130
	v_ashrrev_i32_e32 v197, 7, v130
	v_ashrrev_i32_e32 v132, 5, v130
	v_lshlrev_b32_e32 v0, 2, v131
	s_lshl_b64 s[48:49], s[12:13], 11
	v_lshlrev_b32_e32 v164, 4, v131
	v_cmp_eq_u32_e64 s[40:41], 0, v131
	v_and_b32_e32 v131, 0x4f, v130
	v_and_b32_e32 v130, 48, v130
	s_movk_i32 s13, 0x210
	v_cmp_lt_i32_e32 vcc, v247, v214
	v_mad_u32_u24 v202, v131, s13, v130
	s_ashr_i32 s47, s46, 31
	v_cndmask_b32_e32 v130, v225, v247, vcc
	v_cmp_lt_i32_e32 vcc, v248, v214
	v_lshlrev_b32_e32 v203, 2, v130
	s_lshl_b32 s69, s57, 1
	v_cndmask_b32_e32 v130, v225, v248, vcc
	v_cmp_lt_i32_e32 vcc, v249, v214
	v_lshlrev_b32_e32 v204, 2, v130
	s_add_u32 s15, s53, s48
	v_cndmask_b32_e32 v130, v225, v249, vcc
	v_cmp_lt_i32_e32 vcc, v223, v214
	v_lshlrev_b32_e32 v205, 2, v130
	v_lshl_or_b32 v0, v132, 10, v0
	v_cndmask_b32_e32 v130, v225, v223, vcc
	v_cmp_lt_i32_e32 vcc, v252, v214
	v_lshlrev_b32_e32 v206, 2, v130
	v_mul_lo_u32 v165, v132, s13
	v_cndmask_b32_e32 v130, v225, v252, vcc
	v_lshlrev_b32_e32 v207, 2, v130
	v_add_u32_e32 v130, s12, v132
	v_ashrrev_i32_e32 v131, 31, v130
	v_lshlrev_b64 v[132:133], 5, v[130:131]
	v_add_u32_e32 v134, 8, v130
	v_add_u32_e32 v136, 16, v130
	v_add_u32_e32 v138, 24, v130
	v_add_u32_e32 v140, 32, v130
	v_add_u32_e32 v142, 40, v130
	v_add_u32_e32 v144, 48, v130
	v_add_u32_e32 v146, 56, v130
	v_add_u32_e32 v148, 64, v130
	v_add_u32_e32 v150, 0x48, v130
	v_add_u32_e32 v152, 0x50, v130
	v_add_u32_e32 v154, 0x58, v130
	v_add_u32_e32 v156, 0x60, v130
	v_add_u32_e32 v158, 0x68, v130
	v_add_u32_e32 v160, 0x70, v130
	v_add_u32_e32 v130, 0x78, v130
	s_addc_u32 s48, s54, s49
	s_lshl_b64 s[12:13], s[46:47], 1
	v_ashrrev_i32_e32 v135, 31, v134
	v_ashrrev_i32_e32 v137, 31, v136
	v_ashrrev_i32_e32 v139, 31, v138
	v_ashrrev_i32_e32 v141, 31, v140
	v_ashrrev_i32_e32 v143, 31, v142
	v_ashrrev_i32_e32 v145, 31, v144
	v_ashrrev_i32_e32 v147, 31, v146
	v_ashrrev_i32_e32 v149, 31, v148
	v_ashrrev_i32_e32 v151, 31, v150
	v_ashrrev_i32_e32 v153, 31, v152
	v_ashrrev_i32_e32 v155, 31, v154
	v_ashrrev_i32_e32 v157, 31, v156
	v_ashrrev_i32_e32 v159, 31, v158
	v_ashrrev_i32_e32 v161, 31, v160
	v_ashrrev_i32_e32 v131, 31, v130
	s_add_u32 s12, s15, s12
	v_lshlrev_b64 v[134:135], 5, v[134:135]
	v_lshlrev_b64 v[136:137], 5, v[136:137]
	v_lshlrev_b64 v[138:139], 5, v[138:139]
	v_lshlrev_b64 v[140:141], 5, v[140:141]
	v_lshlrev_b64 v[142:143], 5, v[142:143]
	v_lshlrev_b64 v[144:145], 5, v[144:145]
	v_lshlrev_b64 v[146:147], 5, v[146:147]
	v_lshlrev_b64 v[148:149], 5, v[148:149]
	v_lshlrev_b64 v[150:151], 5, v[150:151]
	v_lshlrev_b64 v[152:153], 5, v[152:153]
	v_lshlrev_b64 v[154:155], 5, v[154:155]
	v_lshlrev_b64 v[156:157], 5, v[156:157]
	v_lshlrev_b64 v[158:159], 5, v[158:159]
	v_lshlrev_b64 v[160:161], 5, v[160:161]
	v_lshlrev_b64 v[162:163], 5, v[130:131]
	s_addc_u32 s13, s48, s13
	s_mov_b32 s14, 0
	v_lshl_add_u64 v[130:131], v[0:1], 1, s[12:13]
	v_lshl_add_u64 v[132:133], s[42:43], 0, v[132:133]
	v_lshl_add_u64 v[134:135], s[42:43], 0, v[134:135]
	v_lshl_add_u64 v[136:137], s[42:43], 0, v[136:137]
	v_lshl_add_u64 v[138:139], s[42:43], 0, v[138:139]
	v_lshl_add_u64 v[140:141], s[42:43], 0, v[140:141]
	v_lshl_add_u64 v[142:143], s[42:43], 0, v[142:143]
	v_lshl_add_u64 v[144:145], s[42:43], 0, v[144:145]
	v_lshl_add_u64 v[146:147], s[42:43], 0, v[146:147]
	v_lshl_add_u64 v[148:149], s[42:43], 0, v[148:149]
	v_lshl_add_u64 v[150:151], s[42:43], 0, v[150:151]
	v_lshl_add_u64 v[152:153], s[42:43], 0, v[152:153]
	v_lshl_add_u64 v[154:155], s[42:43], 0, v[154:155]
	v_lshl_add_u64 v[156:157], s[42:43], 0, v[156:157]
	v_lshl_add_u64 v[158:159], s[42:43], 0, v[158:159]
	v_lshl_add_u64 v[160:161], s[42:43], 0, v[160:161]
	v_lshl_add_u64 v[162:163], s[42:43], 0, v[162:163]
	s_mov_b64 s[46:47], -1
	v_add_u32_e32 v0, v164, v165
	v_mov_b32_e32 v243, 0x7f800000
	s_branch .LBB0_197

.LBB0_702:
	s_or_b64 exec, exec, s[14:15]
	s_waitcnt lgkmcnt(0)
	s_add_u32 s69, s86, s46
	s_addc_u32 s79, s87, s47
	s_movk_i32 s14, 0x104
	s_cmp_gt_i32 s53, -1
	s_mov_b32 s94, s53
	v_mul_lo_u32 v0, v37, s14
	s_cselect_b64 s[46:47], -1, 0
	s_lshl_b64 s[14:15], s[94:95], 3
	v_readlane_b32 s44, v253, 0
	v_readlane_b32 s45, v253, 1
	s_add_u32 s70, s44, s14
	s_addc_u32 s71, s45, s15
	s_ashr_i32 s55, s54, 31
	s_ashr_i32 s49, s48, 31
	v_lshl_add_u32 v0, v36, 2, v0
	s_cmp_eq_u32 s52, 0
	s_waitcnt vmcnt(0)
	ds_write2_b32 v0, v6, v7 offset1:1
	ds_write2_b32 v0, v8, v9 offset0:2 offset1:3
	v_add_u32_e32 v6, 0x1040, v0
	s_cselect_b64 s[44:45], -1, 0
	s_add_i32 s14, s68, 0xfffff540
	ds_write2_b32 v6, v2, v3 offset1:1
	v_add_u32_e32 v2, 0x1048, v0
	s_lshr_b32 s14, s14, 6
	ds_write2_b32 v2, v4, v5 offset1:1
	v_add_u32_e32 v2, 0x2080, v0
	s_cmp_gt_i32 s78, 42
	ds_write2_b32 v2, v14, v15 offset1:1
	v_add_u32_e32 v2, 0x2088, v0
	s_cselect_b32 s14, s14, s78
	ds_write2_b32 v2, v16, v17 offset1:1
	v_add_u32_e32 v2, 0x30c0, v0
	v_add_u32_e32 v0, 0x30c8, v0
	s_cselect_b32 s15, 64, 0
	s_lshl_b32 s14, s14, 7
	ds_write2_b32 v0, v12, v13 offset1:1
	v_lshlrev_b32_e32 v0, 3, v35
	s_or_b32 s14, s14, s15
	s_lshl_b64 s[52:53], s[48:49], 1
	v_ashrrev_i32_e32 v13, 3, v35
	v_and_b32_e32 v12, 56, v0
	s_add_u32 s52, s69, s52
	s_addc_u32 s53, s79, s53
	v_lshlrev_b32_e32 v0, 1, v12
	v_add_u32_e32 v14, s68, v13
	v_cndmask_b32_e64 v4, 0, 1, s[46:47]
	ds_write2_b32 v2, v10, v11 offset1:1
	v_lshl_add_u64 v[2:3], s[52:53], 0, v[0:1]
	s_mov_b32 s100, s12
	s_cmpk_eq_u32 s12, 0x400
	s_cbranch_scc1 .Lmy_kb_do
	s_cmpk_eq_u32 s12, 0xac0
	s_cbranch_scc0 .Lmy_kb_skip
